# attention: all hand-scheduling options together (diagonal-step body, rotated back edge, spread softmax, prefetches, defer8 stagger)
# speedup vs baseline: 1.0094x; 1.0038x over previous
.LBB0_107:
	s_cmp_lt_u32 s42, s98
	s_cbranch_scc1 .Lnd_107
	s_and_b32 s33, s42, 1
	s_mul_i32 s6, s33, 0x9000
	v_add_u32_e32 v199, s6, v187
	v_add_u32_e32 v198, s6, v188
	s_mov_b64 s[54:55], exec
	v_readfirstlane_b32 s32, v195
	s_sub_i32 s32, s32, 31
	s_add_i32 s4, s97, 0
	s_cmp_gt_i32 s4, s32
	s_cbranch_scc1 .Lmk_skip0
	s_cmp_eq_u32 s4, s32
	s_cbranch_scc1 .Lmk_diag0
	ds_read_b128 v[216:219], v199 offset:0
	ds_read_b128 v[232:235], v193 offset:0
	ds_read_b128 v[220:223], v199 offset:32
	ds_read_b128 v[236:239], v193 offset:32
	ds_read_b128 v[224:227], v199 offset:64
	ds_read_b128 v[244:247], v193 offset:64
	ds_read_b128 v[228:231], v199 offset:96
	ds_read_b128 v[248:251], v193 offset:96
	s_waitcnt lgkmcnt(6)
	v_mfma_f32_32x32x16_bf16 v[144:159], v[216:219], v[232:235], v[0:15]
	s_waitcnt lgkmcnt(4)
	v_mfma_f32_32x32x16_bf16 v[144:159], v[220:223], v[236:239], v[144:159]
	s_waitcnt lgkmcnt(2)
	v_mfma_f32_32x32x16_bf16 v[144:159], v[224:227], v[244:247], v[144:159]
	s_waitcnt lgkmcnt(0)
	v_mfma_f32_32x32x16_bf16 v[144:159], v[228:231], v[248:251], v[144:159]
	ds_read_b128 v[216:219], v199 offset:9216
	ds_read_b128 v[232:235], v193 offset:36864
	ds_read_b128 v[220:223], v199 offset:9248
	ds_read_b128 v[236:239], v193 offset:36896
	ds_read_b128 v[224:227], v199 offset:9280
	ds_read_b128 v[244:247], v193 offset:36928
	ds_read_b128 v[228:231], v199 offset:9312
	ds_read_b128 v[248:251], v193 offset:36960
	s_nop 3
	v_exp_f32_e32 v144, v144
	v_exp_f32_e32 v145, v145
	v_exp_f32_e32 v146, v146
	v_add_f32_e32 v243, v144, v145
	v_exp_f32_e32 v147, v147
	v_add_f32_e32 v243, v146, v243
	v_exp_f32_e32 v148, v148
	v_add_f32_e32 v243, v147, v243
	v_exp_f32_e32 v149, v149
	v_add_f32_e32 v243, v148, v243
	v_exp_f32_e32 v150, v150
	v_add_f32_e32 v243, v149, v243
	v_exp_f32_e32 v151, v151
	v_add_f32_e32 v243, v150, v243
	v_exp_f32_e32 v152, v152
	v_add_f32_e32 v243, v151, v243
	v_exp_f32_e32 v153, v153
	v_add_f32_e32 v243, v152, v243
	v_exp_f32_e32 v154, v154
	v_add_f32_e32 v243, v153, v243
	v_exp_f32_e32 v155, v155
	v_add_f32_e32 v243, v154, v243
	v_exp_f32_e32 v156, v156
	v_add_f32_e32 v243, v155, v243
	s_waitcnt lgkmcnt(6)
	v_mfma_f32_32x32x16_bf16 v[200:215], v[216:219], v[232:235], v[0:15]
	v_exp_f32_e32 v157, v157
	v_add_f32_e32 v243, v156, v243
	v_exp_f32_e32 v158, v158
	v_add_f32_e32 v243, v157, v243
	s_waitcnt lgkmcnt(4)
	v_mfma_f32_32x32x16_bf16 v[200:215], v[220:223], v[236:239], v[200:215]
	v_exp_f32_e32 v159, v159
	v_add_f32_e32 v243, v158, v243
	v_add_f32_e32 v243, v159, v243
	v_add_f32_e32 v196, v196, v243
	s_waitcnt lgkmcnt(2)
	v_mfma_f32_32x32x16_bf16 v[200:215], v[224:227], v[244:247], v[200:215]
	v_cvt_pk_bf16_f32 v144, v144, v145
	v_cvt_pk_bf16_f32 v145, v146, v147
	v_cvt_pk_bf16_f32 v146, v148, v149
	v_cvt_pk_bf16_f32 v147, v150, v151
	s_waitcnt lgkmcnt(0)
	v_mfma_f32_32x32x16_bf16 v[200:215], v[228:231], v[248:251], v[200:215]
	ds_read_b128 v[216:219], v198 offset:0
	ds_read_b128 v[224:227], v198 offset:4608
	ds_read_b128 v[232:235], v198 offset:9216
	ds_read_b128 v[244:247], v198 offset:13824
	ds_read_b128 v[220:223], v198 offset:32
	ds_read_b128 v[228:231], v198 offset:4640
	ds_read_b128 v[236:239], v198 offset:9248
	ds_read_b128 v[248:251], v198 offset:13856
	v_cvt_pk_bf16_f32 v148, v152, v153
	v_cvt_pk_bf16_f32 v149, v154, v155
	v_cvt_pk_bf16_f32 v150, v156, v157
	v_cvt_pk_bf16_f32 v151, v158, v159
	s_waitcnt lgkmcnt(7)
	v_mfma_f32_32x32x16_bf16 v[112:127], v[216:219], v[144:147], v[112:127]
	v_exp_f32_e32 v200, v200
	v_exp_f32_e32 v201, v201
	v_exp_f32_e32 v202, v202
	s_waitcnt lgkmcnt(6)
	v_mfma_f32_32x32x16_bf16 v[80:95], v[224:227], v[144:147], v[80:95]
	v_add_f32_e32 v243, v200, v201
	v_exp_f32_e32 v203, v203
	v_add_f32_e32 v243, v202, v243
	s_waitcnt lgkmcnt(5)
	v_mfma_f32_32x32x16_bf16 v[48:63], v[232:235], v[144:147], v[48:63]
	v_exp_f32_e32 v204, v204
	v_add_f32_e32 v243, v203, v243
	v_exp_f32_e32 v205, v205
	s_waitcnt lgkmcnt(4)
	v_mfma_f32_32x32x16_bf16 v[16:31], v[244:247], v[144:147], v[16:31]
	v_add_f32_e32 v243, v204, v243
	v_exp_f32_e32 v206, v206
	v_add_f32_e32 v243, v205, v243
	s_waitcnt lgkmcnt(3)
	v_mfma_f32_32x32x16_bf16 v[112:127], v[220:223], v[148:151], v[112:127]
	v_exp_f32_e32 v207, v207
	v_add_f32_e32 v243, v206, v243
	v_exp_f32_e32 v208, v208
	s_waitcnt lgkmcnt(2)
	v_mfma_f32_32x32x16_bf16 v[80:95], v[228:231], v[148:151], v[80:95]
	v_add_f32_e32 v243, v207, v243
	v_cvt_pk_bf16_f32 v200, v200, v201
	v_cvt_pk_bf16_f32 v201, v202, v203
	s_waitcnt lgkmcnt(1)
	v_mfma_f32_32x32x16_bf16 v[48:63], v[236:239], v[148:151], v[48:63]
	v_cvt_pk_bf16_f32 v202, v204, v205
	v_cvt_pk_bf16_f32 v203, v206, v207
	v_exp_f32_e32 v209, v209
	s_waitcnt lgkmcnt(0)
	v_mfma_f32_32x32x16_bf16 v[16:31], v[248:251], v[148:151], v[16:31]
	v_add_f32_e32 v243, v208, v243
	v_exp_f32_e32 v210, v210
	v_add_f32_e32 v243, v209, v243
	v_mfma_f32_32x32x16_bf16 v[128:143], v[216:219], v[200:203], v[128:143]
	v_exp_f32_e32 v211, v211
	v_add_f32_e32 v243, v210, v243
	v_exp_f32_e32 v212, v212
	v_add_f32_e32 v243, v211, v243
	v_mfma_f32_32x32x16_bf16 v[96:111], v[224:227], v[200:203], v[96:111]
	v_exp_f32_e32 v213, v213
	v_add_f32_e32 v243, v212, v243
	v_exp_f32_e32 v214, v214
	v_add_f32_e32 v243, v213, v243
	v_mfma_f32_32x32x16_bf16 v[64:79], v[232:235], v[200:203], v[64:79]
	v_exp_f32_e32 v215, v215
	v_add_f32_e32 v243, v214, v243
	v_add_f32_e32 v243, v215, v243
	v_add_f32_e32 v197, v197, v243
	v_mfma_f32_32x32x16_bf16 v[32:47], v[244:247], v[200:203], v[32:47]
	v_cvt_pk_bf16_f32 v204, v208, v209
	v_cvt_pk_bf16_f32 v205, v210, v211
	v_cvt_pk_bf16_f32 v206, v212, v213
	v_cvt_pk_bf16_f32 v207, v214, v215
	s_nop 1
	v_mfma_f32_32x32x16_bf16 v[128:143], v[220:223], v[204:207], v[128:143]
	v_mfma_f32_32x32x16_bf16 v[96:111], v[228:231], v[204:207], v[96:111]
	v_mfma_f32_32x32x16_bf16 v[64:79], v[236:239], v[204:207], v[64:79]
	v_mfma_f32_32x32x16_bf16 v[32:47], v[248:251], v[204:207], v[32:47]
	s_branch .Lmk_skip0

.Lmk_skip0:
	s_add_i32 s4, s97, 32
	s_cmp_gt_i32 s4, s32
	s_cbranch_scc1 .Lmk_skip1
	s_cmp_eq_u32 s4, s32
	s_cbranch_scc1 .Lmk_diag1
	ds_read_b128 v[216:219], v199 offset:4608
	ds_read_b128 v[232:235], v193 offset:0
	ds_read_b128 v[220:223], v199 offset:4640
	ds_read_b128 v[236:239], v193 offset:32
	ds_read_b128 v[224:227], v199 offset:4672
	ds_read_b128 v[244:247], v193 offset:64
	ds_read_b128 v[228:231], v199 offset:4704
	ds_read_b128 v[248:251], v193 offset:96
	s_waitcnt lgkmcnt(6)
	v_mfma_f32_32x32x16_bf16 v[144:159], v[216:219], v[232:235], v[0:15]
	s_waitcnt lgkmcnt(4)
	v_mfma_f32_32x32x16_bf16 v[144:159], v[220:223], v[236:239], v[144:159]
	s_waitcnt lgkmcnt(2)
	v_mfma_f32_32x32x16_bf16 v[144:159], v[224:227], v[244:247], v[144:159]
	s_waitcnt lgkmcnt(0)
	v_mfma_f32_32x32x16_bf16 v[144:159], v[228:231], v[248:251], v[144:159]
	ds_read_b128 v[216:219], v199 offset:13824
	ds_read_b128 v[232:235], v193 offset:36864
	ds_read_b128 v[220:223], v199 offset:13856
	ds_read_b128 v[236:239], v193 offset:36896
	ds_read_b128 v[224:227], v199 offset:13888
	ds_read_b128 v[244:247], v193 offset:36928
	ds_read_b128 v[228:231], v199 offset:13920
	ds_read_b128 v[248:251], v193 offset:36960
	s_nop 3
	v_exp_f32_e32 v144, v144
	v_exp_f32_e32 v145, v145
	v_exp_f32_e32 v146, v146
	v_add_f32_e32 v243, v144, v145
	v_exp_f32_e32 v147, v147
	v_add_f32_e32 v243, v146, v243
	v_exp_f32_e32 v148, v148
	v_add_f32_e32 v243, v147, v243
	v_exp_f32_e32 v149, v149
	v_add_f32_e32 v243, v148, v243
	v_exp_f32_e32 v150, v150
	v_add_f32_e32 v243, v149, v243
	v_exp_f32_e32 v151, v151
	v_add_f32_e32 v243, v150, v243
	v_exp_f32_e32 v152, v152
	v_add_f32_e32 v243, v151, v243
	v_exp_f32_e32 v153, v153
	v_add_f32_e32 v243, v152, v243
	v_exp_f32_e32 v154, v154
	v_add_f32_e32 v243, v153, v243
	v_exp_f32_e32 v155, v155
	v_add_f32_e32 v243, v154, v243
	v_exp_f32_e32 v156, v156
	v_add_f32_e32 v243, v155, v243
	s_waitcnt lgkmcnt(6)
	v_mfma_f32_32x32x16_bf16 v[200:215], v[216:219], v[232:235], v[0:15]
	v_exp_f32_e32 v157, v157
	v_add_f32_e32 v243, v156, v243
	v_exp_f32_e32 v158, v158
	v_add_f32_e32 v243, v157, v243
	s_waitcnt lgkmcnt(4)
	v_mfma_f32_32x32x16_bf16 v[200:215], v[220:223], v[236:239], v[200:215]
	v_exp_f32_e32 v159, v159
	v_add_f32_e32 v243, v158, v243
	v_add_f32_e32 v243, v159, v243
	v_add_f32_e32 v196, v196, v243
	s_waitcnt lgkmcnt(2)
	v_mfma_f32_32x32x16_bf16 v[200:215], v[224:227], v[244:247], v[200:215]
	v_cvt_pk_bf16_f32 v144, v144, v145
	v_cvt_pk_bf16_f32 v145, v146, v147
	v_cvt_pk_bf16_f32 v146, v148, v149
	v_cvt_pk_bf16_f32 v147, v150, v151
	s_waitcnt lgkmcnt(0)
	v_mfma_f32_32x32x16_bf16 v[200:215], v[228:231], v[248:251], v[200:215]
	ds_read_b128 v[216:219], v198 offset:64
	ds_read_b128 v[224:227], v198 offset:4672
	ds_read_b128 v[232:235], v198 offset:9280
	ds_read_b128 v[244:247], v198 offset:13888
	ds_read_b128 v[220:223], v198 offset:96
	ds_read_b128 v[228:231], v198 offset:4704
	ds_read_b128 v[236:239], v198 offset:9312
	ds_read_b128 v[248:251], v198 offset:13920
	v_cvt_pk_bf16_f32 v148, v152, v153
	v_cvt_pk_bf16_f32 v149, v154, v155
	v_cvt_pk_bf16_f32 v150, v156, v157
	v_cvt_pk_bf16_f32 v151, v158, v159
	s_waitcnt lgkmcnt(7)
	v_mfma_f32_32x32x16_bf16 v[112:127], v[216:219], v[144:147], v[112:127]
	v_exp_f32_e32 v200, v200
	v_exp_f32_e32 v201, v201
	v_exp_f32_e32 v202, v202
	s_waitcnt lgkmcnt(6)
	v_mfma_f32_32x32x16_bf16 v[80:95], v[224:227], v[144:147], v[80:95]
	v_add_f32_e32 v243, v200, v201
	v_exp_f32_e32 v203, v203
	v_add_f32_e32 v243, v202, v243
	s_waitcnt lgkmcnt(5)
	v_mfma_f32_32x32x16_bf16 v[48:63], v[232:235], v[144:147], v[48:63]
	v_exp_f32_e32 v204, v204
	v_add_f32_e32 v243, v203, v243
	v_exp_f32_e32 v205, v205
	s_waitcnt lgkmcnt(4)
	v_mfma_f32_32x32x16_bf16 v[16:31], v[244:247], v[144:147], v[16:31]
	v_add_f32_e32 v243, v204, v243
	v_exp_f32_e32 v206, v206
	v_add_f32_e32 v243, v205, v243
	s_waitcnt lgkmcnt(3)
	v_mfma_f32_32x32x16_bf16 v[112:127], v[220:223], v[148:151], v[112:127]
	v_exp_f32_e32 v207, v207
	v_add_f32_e32 v243, v206, v243
	v_exp_f32_e32 v208, v208
	s_waitcnt lgkmcnt(2)
	v_mfma_f32_32x32x16_bf16 v[80:95], v[228:231], v[148:151], v[80:95]
	v_add_f32_e32 v243, v207, v243
	v_cvt_pk_bf16_f32 v200, v200, v201
	v_cvt_pk_bf16_f32 v201, v202, v203
	s_waitcnt lgkmcnt(1)
	v_mfma_f32_32x32x16_bf16 v[48:63], v[236:239], v[148:151], v[48:63]
	v_cvt_pk_bf16_f32 v202, v204, v205
	v_cvt_pk_bf16_f32 v203, v206, v207
	v_exp_f32_e32 v209, v209
	s_waitcnt lgkmcnt(0)
	v_mfma_f32_32x32x16_bf16 v[16:31], v[248:251], v[148:151], v[16:31]
	v_add_f32_e32 v243, v208, v243
	v_exp_f32_e32 v210, v210
	v_add_f32_e32 v243, v209, v243
	v_mfma_f32_32x32x16_bf16 v[128:143], v[216:219], v[200:203], v[128:143]
	v_exp_f32_e32 v211, v211
	v_add_f32_e32 v243, v210, v243
	v_exp_f32_e32 v212, v212
	v_add_f32_e32 v243, v211, v243
	v_mfma_f32_32x32x16_bf16 v[96:111], v[224:227], v[200:203], v[96:111]
	v_exp_f32_e32 v213, v213
	v_add_f32_e32 v243, v212, v243
	v_exp_f32_e32 v214, v214
	v_add_f32_e32 v243, v213, v243
	v_mfma_f32_32x32x16_bf16 v[64:79], v[232:235], v[200:203], v[64:79]
	v_exp_f32_e32 v215, v215
	v_add_f32_e32 v243, v214, v243
	v_add_f32_e32 v243, v215, v243
	v_add_f32_e32 v197, v197, v243
	v_mfma_f32_32x32x16_bf16 v[32:47], v[244:247], v[200:203], v[32:47]
	v_cvt_pk_bf16_f32 v204, v208, v209
	v_cvt_pk_bf16_f32 v205, v210, v211
	v_cvt_pk_bf16_f32 v206, v212, v213
	v_cvt_pk_bf16_f32 v207, v214, v215
	s_nop 1
	v_mfma_f32_32x32x16_bf16 v[128:143], v[220:223], v[204:207], v[128:143]
	v_mfma_f32_32x32x16_bf16 v[96:111], v[228:231], v[204:207], v[96:111]
	v_mfma_f32_32x32x16_bf16 v[64:79], v[236:239], v[204:207], v[64:79]
	v_mfma_f32_32x32x16_bf16 v[32:47], v[248:251], v[204:207], v[32:47]
	s_branch .Lmk_skip1

.Lq_A:
	ds_read_b128 v[216:219], v199 offset:0
	ds_read_b128 v[232:235], v193 offset:0
	ds_read_b128 v[220:223], v199 offset:32
	ds_read_b128 v[236:239], v193 offset:32
	ds_read_b128 v[224:227], v199 offset:64
	ds_read_b128 v[244:247], v193 offset:64
	ds_read_b128 v[228:231], v199 offset:96
	ds_read_b128 v[248:251], v193 offset:96
	s_waitcnt lgkmcnt(6)
	v_mfma_f32_32x32x16_bf16 v[144:159], v[216:219], v[232:235], v[0:15]
	s_waitcnt lgkmcnt(4)
	v_mfma_f32_32x32x16_bf16 v[144:159], v[220:223], v[236:239], v[144:159]
	s_waitcnt lgkmcnt(2)
	v_mfma_f32_32x32x16_bf16 v[144:159], v[224:227], v[244:247], v[144:159]
	s_waitcnt lgkmcnt(0)
	v_mfma_f32_32x32x16_bf16 v[144:159], v[228:231], v[248:251], v[144:159]
	ds_read_b128 v[216:219], v199 offset:9216
	ds_read_b128 v[232:235], v193 offset:36864
	ds_read_b128 v[220:223], v199 offset:9248
	ds_read_b128 v[236:239], v193 offset:36896
	ds_read_b128 v[224:227], v199 offset:9280
	ds_read_b128 v[244:247], v193 offset:36928
	ds_read_b128 v[228:231], v199 offset:9312
	ds_read_b128 v[248:251], v193 offset:36960
	s_nop 3
	v_exp_f32_e32 v144, v144
	v_exp_f32_e32 v145, v145
	v_exp_f32_e32 v146, v146
	v_add_f32_e32 v243, v144, v145
	v_exp_f32_e32 v147, v147
	v_add_f32_e32 v243, v146, v243
	v_exp_f32_e32 v148, v148
	v_add_f32_e32 v243, v147, v243
	v_exp_f32_e32 v149, v149
	v_add_f32_e32 v243, v148, v243
	v_exp_f32_e32 v150, v150
	v_add_f32_e32 v243, v149, v243
	v_exp_f32_e32 v151, v151
	v_add_f32_e32 v243, v150, v243
	v_exp_f32_e32 v152, v152
	v_add_f32_e32 v243, v151, v243
	v_exp_f32_e32 v153, v153
	v_add_f32_e32 v243, v152, v243
	v_exp_f32_e32 v154, v154
	v_add_f32_e32 v243, v153, v243
	v_exp_f32_e32 v155, v155
	v_add_f32_e32 v243, v154, v243
	v_exp_f32_e32 v156, v156
	v_add_f32_e32 v243, v155, v243
	s_waitcnt lgkmcnt(6)
	v_mfma_f32_32x32x16_bf16 v[200:215], v[216:219], v[232:235], v[0:15]
	v_exp_f32_e32 v157, v157
	v_add_f32_e32 v243, v156, v243
	v_exp_f32_e32 v158, v158
	v_add_f32_e32 v243, v157, v243
	s_waitcnt lgkmcnt(4)
	v_mfma_f32_32x32x16_bf16 v[200:215], v[220:223], v[236:239], v[200:215]
	v_exp_f32_e32 v159, v159
	v_add_f32_e32 v243, v158, v243
	v_add_f32_e32 v243, v159, v243
	v_add_f32_e32 v196, v196, v243
	s_waitcnt lgkmcnt(2)
	v_mfma_f32_32x32x16_bf16 v[200:215], v[224:227], v[244:247], v[200:215]
	v_cvt_pk_bf16_f32 v144, v144, v145
	v_cvt_pk_bf16_f32 v145, v146, v147
	v_cvt_pk_bf16_f32 v146, v148, v149
	v_cvt_pk_bf16_f32 v147, v150, v151
	s_waitcnt lgkmcnt(0)
	v_mfma_f32_32x32x16_bf16 v[200:215], v[228:231], v[248:251], v[200:215]
	ds_read_b128 v[216:219], v198 offset:0
	ds_read_b128 v[224:227], v198 offset:4608
	ds_read_b128 v[232:235], v198 offset:9216
	ds_read_b128 v[244:247], v198 offset:13824
	ds_read_b128 v[220:223], v198 offset:32
	ds_read_b128 v[228:231], v198 offset:4640
	ds_read_b128 v[236:239], v198 offset:9248
	ds_read_b128 v[248:251], v198 offset:13856
	v_cvt_pk_bf16_f32 v148, v152, v153
	v_cvt_pk_bf16_f32 v149, v154, v155
	v_cvt_pk_bf16_f32 v150, v156, v157
	v_cvt_pk_bf16_f32 v151, v158, v159
	s_waitcnt lgkmcnt(7)
	v_mfma_f32_32x32x16_bf16 v[112:127], v[216:219], v[144:147], v[112:127]
	v_exp_f32_e32 v200, v200
	v_exp_f32_e32 v201, v201
	v_exp_f32_e32 v202, v202
	s_waitcnt lgkmcnt(6)
	v_mfma_f32_32x32x16_bf16 v[80:95], v[224:227], v[144:147], v[80:95]
	v_add_f32_e32 v243, v200, v201
	v_exp_f32_e32 v203, v203
	v_add_f32_e32 v243, v202, v243
	s_waitcnt lgkmcnt(5)
	v_mfma_f32_32x32x16_bf16 v[48:63], v[232:235], v[144:147], v[48:63]
	v_exp_f32_e32 v204, v204
	v_add_f32_e32 v243, v203, v243
	v_exp_f32_e32 v205, v205
	s_waitcnt lgkmcnt(4)
	v_mfma_f32_32x32x16_bf16 v[16:31], v[244:247], v[144:147], v[16:31]
	v_add_f32_e32 v243, v204, v243
	v_exp_f32_e32 v206, v206
	v_add_f32_e32 v243, v205, v243
	s_waitcnt lgkmcnt(3)
	v_mfma_f32_32x32x16_bf16 v[112:127], v[220:223], v[148:151], v[112:127]
	v_exp_f32_e32 v207, v207
	v_add_f32_e32 v243, v206, v243
	v_exp_f32_e32 v208, v208
	s_waitcnt lgkmcnt(2)
	v_mfma_f32_32x32x16_bf16 v[80:95], v[228:231], v[148:151], v[80:95]
	v_add_f32_e32 v243, v207, v243
	v_cvt_pk_bf16_f32 v200, v200, v201
	v_cvt_pk_bf16_f32 v201, v202, v203
	s_waitcnt lgkmcnt(1)
	v_mfma_f32_32x32x16_bf16 v[48:63], v[236:239], v[148:151], v[48:63]
	v_cvt_pk_bf16_f32 v202, v204, v205
	v_cvt_pk_bf16_f32 v203, v206, v207
	v_exp_f32_e32 v209, v209
	s_waitcnt lgkmcnt(0)
	v_mfma_f32_32x32x16_bf16 v[16:31], v[248:251], v[148:151], v[16:31]
	v_add_f32_e32 v243, v208, v243
	v_exp_f32_e32 v210, v210
	v_add_f32_e32 v243, v209, v243
	v_mfma_f32_32x32x16_bf16 v[128:143], v[216:219], v[200:203], v[128:143]
	v_exp_f32_e32 v211, v211
	v_add_f32_e32 v243, v210, v243
	v_exp_f32_e32 v212, v212
	v_add_f32_e32 v243, v211, v243
	v_mfma_f32_32x32x16_bf16 v[96:111], v[224:227], v[200:203], v[96:111]
	v_exp_f32_e32 v213, v213
	v_add_f32_e32 v243, v212, v243
	v_exp_f32_e32 v214, v214
	v_add_f32_e32 v243, v213, v243
	v_mfma_f32_32x32x16_bf16 v[64:79], v[232:235], v[200:203], v[64:79]
	v_exp_f32_e32 v215, v215
	v_add_f32_e32 v243, v214, v243
	v_add_f32_e32 v243, v215, v243
	v_add_f32_e32 v197, v197, v243
	v_mfma_f32_32x32x16_bf16 v[32:47], v[244:247], v[200:203], v[32:47]
	v_cvt_pk_bf16_f32 v204, v208, v209
	v_cvt_pk_bf16_f32 v205, v210, v211
	v_cvt_pk_bf16_f32 v206, v212, v213
	v_cvt_pk_bf16_f32 v207, v214, v215
	ds_read_b128 v[252:255], v199 offset:4608
	ds_read_b128 v[208:211], v193
	ds_read_b128 v[212:215], v199 offset:4640
	v_mfma_f32_32x32x16_bf16 v[128:143], v[220:223], v[204:207], v[128:143]
	v_mfma_f32_32x32x16_bf16 v[96:111], v[228:231], v[204:207], v[96:111]
	v_mfma_f32_32x32x16_bf16 v[64:79], v[236:239], v[204:207], v[64:79]
	v_mfma_f32_32x32x16_bf16 v[32:47], v[248:251], v[204:207], v[32:47]
	ds_read_b128 v[236:239], v193 offset:32
	ds_read_b128 v[224:227], v199 offset:4672
	ds_read_b128 v[244:247], v193 offset:64
	ds_read_b128 v[228:231], v199 offset:4704
	ds_read_b128 v[248:251], v193 offset:96
	s_waitcnt lgkmcnt(6)
	v_mfma_f32_32x32x16_bf16 v[144:159], v[252:255], v[208:211], v[0:15]
	s_waitcnt lgkmcnt(4)
	v_mfma_f32_32x32x16_bf16 v[144:159], v[212:215], v[236:239], v[144:159]
	s_waitcnt lgkmcnt(2)
	v_mfma_f32_32x32x16_bf16 v[144:159], v[224:227], v[244:247], v[144:159]
	s_waitcnt lgkmcnt(0)
	v_mfma_f32_32x32x16_bf16 v[144:159], v[228:231], v[248:251], v[144:159]
	ds_read_b128 v[216:219], v199 offset:13824
	ds_read_b128 v[232:235], v193 offset:36864
	ds_read_b128 v[220:223], v199 offset:13856
	ds_read_b128 v[236:239], v193 offset:36896
	ds_read_b128 v[224:227], v199 offset:13888
	ds_read_b128 v[244:247], v193 offset:36928
	ds_read_b128 v[228:231], v199 offset:13920
	ds_read_b128 v[248:251], v193 offset:36960
	s_nop 3
	v_exp_f32_e32 v144, v144
	v_exp_f32_e32 v145, v145
	v_exp_f32_e32 v146, v146
	v_add_f32_e32 v243, v144, v145
	v_exp_f32_e32 v147, v147
	v_add_f32_e32 v243, v146, v243
	v_exp_f32_e32 v148, v148
	v_add_f32_e32 v243, v147, v243
	v_exp_f32_e32 v149, v149
	v_add_f32_e32 v243, v148, v243
	v_exp_f32_e32 v150, v150
	v_add_f32_e32 v243, v149, v243
	v_exp_f32_e32 v151, v151
	v_add_f32_e32 v243, v150, v243
	v_exp_f32_e32 v152, v152
	v_add_f32_e32 v243, v151, v243
	v_exp_f32_e32 v153, v153
	v_add_f32_e32 v243, v152, v243
	v_exp_f32_e32 v154, v154
	v_add_f32_e32 v243, v153, v243
	v_exp_f32_e32 v155, v155
	v_add_f32_e32 v243, v154, v243
	v_exp_f32_e32 v156, v156
	v_add_f32_e32 v243, v155, v243
	s_waitcnt lgkmcnt(6)
	v_mfma_f32_32x32x16_bf16 v[200:215], v[216:219], v[232:235], v[0:15]
	v_exp_f32_e32 v157, v157
	v_add_f32_e32 v243, v156, v243
	v_exp_f32_e32 v158, v158
	v_add_f32_e32 v243, v157, v243
	s_waitcnt lgkmcnt(4)
	v_mfma_f32_32x32x16_bf16 v[200:215], v[220:223], v[236:239], v[200:215]
	v_exp_f32_e32 v159, v159
	v_add_f32_e32 v243, v158, v243
	v_add_f32_e32 v243, v159, v243
	v_add_f32_e32 v196, v196, v243
	s_waitcnt lgkmcnt(2)
	v_mfma_f32_32x32x16_bf16 v[200:215], v[224:227], v[244:247], v[200:215]
	v_cvt_pk_bf16_f32 v144, v144, v145
	v_cvt_pk_bf16_f32 v145, v146, v147
	v_cvt_pk_bf16_f32 v146, v148, v149
	v_cvt_pk_bf16_f32 v147, v150, v151
	s_waitcnt lgkmcnt(0)
	v_mfma_f32_32x32x16_bf16 v[200:215], v[228:231], v[248:251], v[200:215]
	ds_read_b128 v[216:219], v198 offset:64
	ds_read_b128 v[224:227], v198 offset:4672
	ds_read_b128 v[232:235], v198 offset:9280
	ds_read_b128 v[244:247], v198 offset:13888
	ds_read_b128 v[220:223], v198 offset:96
	ds_read_b128 v[228:231], v198 offset:4704
	ds_read_b128 v[236:239], v198 offset:9312
	ds_read_b128 v[248:251], v198 offset:13920
	v_cvt_pk_bf16_f32 v148, v152, v153
	v_cvt_pk_bf16_f32 v149, v154, v155
	v_cvt_pk_bf16_f32 v150, v156, v157
	v_cvt_pk_bf16_f32 v151, v158, v159
	s_waitcnt lgkmcnt(7)
	v_mfma_f32_32x32x16_bf16 v[112:127], v[216:219], v[144:147], v[112:127]
	v_exp_f32_e32 v200, v200
	v_exp_f32_e32 v201, v201
	v_exp_f32_e32 v202, v202
	v_add_f32_e32 v243, v200, v201
	v_exp_f32_e32 v203, v203
	s_waitcnt lgkmcnt(6)
	v_mfma_f32_32x32x16_bf16 v[80:95], v[224:227], v[144:147], v[80:95]
	v_add_f32_e32 v243, v202, v243
	v_exp_f32_e32 v204, v204
	v_add_f32_e32 v243, v203, v243
	v_exp_f32_e32 v205, v205
	v_add_f32_e32 v243, v204, v243
	s_waitcnt lgkmcnt(5)
	v_mfma_f32_32x32x16_bf16 v[48:63], v[232:235], v[144:147], v[48:63]
	v_exp_f32_e32 v206, v206
	v_add_f32_e32 v243, v205, v243
	v_exp_f32_e32 v207, v207
	v_add_f32_e32 v243, v206, v243
	v_exp_f32_e32 v208, v208
	s_waitcnt lgkmcnt(4)
	v_mfma_f32_32x32x16_bf16 v[16:31], v[244:247], v[144:147], v[16:31]
	v_add_f32_e32 v243, v207, v243
	v_exp_f32_e32 v209, v209
	v_add_f32_e32 v243, v208, v243
	v_exp_f32_e32 v210, v210
	v_add_f32_e32 v243, v209, v243
	s_waitcnt lgkmcnt(3)
	v_mfma_f32_32x32x16_bf16 v[112:127], v[220:223], v[148:151], v[112:127]
	v_exp_f32_e32 v211, v211
	v_add_f32_e32 v243, v210, v243
	v_exp_f32_e32 v212, v212
	v_add_f32_e32 v243, v211, v243
	v_exp_f32_e32 v213, v213
	s_waitcnt lgkmcnt(2)
	v_mfma_f32_32x32x16_bf16 v[80:95], v[228:231], v[148:151], v[80:95]
	v_add_f32_e32 v243, v212, v243
	v_exp_f32_e32 v214, v214
	v_add_f32_e32 v243, v213, v243
	v_exp_f32_e32 v215, v215
	v_add_f32_e32 v243, v214, v243
	s_waitcnt lgkmcnt(1)
	v_mfma_f32_32x32x16_bf16 v[48:63], v[236:239], v[148:151], v[48:63]
	v_add_f32_e32 v243, v215, v243
	v_add_f32_e32 v197, v197, v243
	v_cvt_pk_bf16_f32 v200, v200, v201
	v_cvt_pk_bf16_f32 v201, v202, v203
	v_cvt_pk_bf16_f32 v202, v204, v205
	s_waitcnt lgkmcnt(0)
	v_mfma_f32_32x32x16_bf16 v[16:31], v[248:251], v[148:151], v[16:31]
	v_cvt_pk_bf16_f32 v203, v206, v207
	v_cvt_pk_bf16_f32 v204, v208, v209
	v_cvt_pk_bf16_f32 v205, v210, v211
	v_cvt_pk_bf16_f32 v206, v212, v213
	v_cvt_pk_bf16_f32 v207, v214, v215
	s_add_i32 s6, s42, 1
	s_waitcnt vmcnt(0)
	s_cmp_eq_u32 s33, 0
	s_cbranch_scc0 .Lqt_s0_1
	v_add_u32_e32 v252, 0x9000, v190
	ds_write_b128 v189, v[160:163] offset:36864
	ds_write2_b64 v252, v[164:165], v[166:167] offset1:2
	ds_write_b128 v189, v[168:171] offset:46080
	v_add_u32_e32 v252, 0xb000, v190
	ds_write2_b64 v252, v[172:173], v[174:175] offset0:128 offset1:130
	s_branch .Lqt_pf_1
